# P5 selected branch: waves with selected blocks in the current stage run at s_setprio 1, others at 0 (work-aware priority)
# speedup vs baseline: 1.0045x; 1.0045x over previous
.LBB0_638:
	s_setprio 0
	s_mov_b64 s[2:3], 0x2000
	v_lshl_add_u64 v[192:193], v[202:203], 0, s[2:3]
	s_mov_b64 s[2:3], 0x4000
	v_lshl_add_u64 v[194:195], v[202:203], 0, s[2:3]
	s_mov_b64 s[2:3], 0x6000
	v_lshl_add_u64 v[190:191], v[202:203], 0, s[2:3]
	global_load_dword v104, v[210:211], off offset:36
	global_load_dwordx4 v[106:109], v[202:203], off
	global_load_dwordx4 v[110:113], v[202:203], off offset:64
	global_load_dwordx4 v[114:117], v[202:203], off offset:128
	global_load_dwordx4 v[118:121], v[202:203], off offset:192
	global_load_dword v105, v[212:213], off offset:36
	global_load_dwordx4 v[122:125], v[192:193], off
	global_load_dwordx4 v[130:133], v[192:193], off offset:64
	global_load_dwordx4 v[134:137], v[192:193], off offset:128
	global_load_dwordx4 v[158:161], v[192:193], off offset:192
	global_load_dword v126, v[196:197], off offset:36
	global_load_dwordx4 v[162:165], v[194:195], off
	global_load_dwordx4 v[166:169], v[194:195], off offset:64
	global_load_dwordx4 v[170:173], v[194:195], off offset:128
	global_load_dwordx4 v[174:177], v[194:195], off offset:192
	global_load_dword v127, v[200:201], off offset:36
	global_load_dwordx4 v[178:181], v[190:191], off
	global_load_dwordx4 v[182:185], v[190:191], off offset:64
	global_load_dwordx4 v[186:189], v[190:191], off offset:128
	global_load_dwordx4 v[248:251], v[190:191], off offset:192
	v_add_f32_e32 v0, 0, v154
	v_add_f32_e32 v4, 0, v150
	v_add_f32_e32 v5, 0, v142
	v_add_f32_e32 v6, 0, v146
	s_mov_b64 s[40:41], 0
	s_waitcnt vmcnt(19)
	v_mul_f32_e32 v1, 0xbfb8aa3b, v104
	v_exp_f32_e32 v1, v1
	s_nop 0
	v_add_f32_e32 v1, 1.0, v1
	v_rcp_f32_e32 v1, v1
	s_nop 0
	v_div_scale_f32 v2, s[2:3], v0, v0, v1
	v_rcp_f32_e32 v3, v2
	s_nop 0
	v_fma_f32 v7, -v2, v3, 1.0
	v_fmac_f32_e32 v3, v7, v3
	v_div_scale_f32 v7, vcc, v1, v0, v1
	v_mul_f32_e32 v56, v7, v3
	v_fma_f32 v57, -v2, v56, v7
	v_fmac_f32_e32 v56, v57, v3
	v_fma_f32 v2, -v2, v56, v7
	v_div_fmas_f32 v2, v2, v3, v56
	v_div_fixup_f32 v2, v2, v0, v1
	v_lshl_add_u64 v[0:1], s[36:37], 0, v[214:215]
	v_lshl_add_u64 v[56:57], v[0:1], 0, v[128:129]
	v_lshlrev_b32_e32 v0, 1, v241
	v_mov_b32_e32 v1, v129
	v_lshl_add_u64 v[68:69], v[56:57], 0, v[0:1]
	s_waitcnt vmcnt(18)
	v_pk_fma_f32 v[56:57], v[100:101], v[2:3], v[106:107] op_sel_hi:[1,0,1]
	v_pk_fma_f32 v[58:59], v[102:103], v[2:3], v[108:109] op_sel_hi:[1,0,1]
	v_cvt_pk_bf16_f32 v56, v56, v57
	v_cvt_pk_bf16_f32 v57, v58, v59
	global_store_dwordx2 v[68:69], v[56:57], off offset:512
	s_waitcnt vmcnt(18)
	v_pk_fma_f32 v[56:57], v[72:73], v[2:3], v[110:111] op_sel_hi:[1,0,1]
	v_pk_fma_f32 v[58:59], v[74:75], v[2:3], v[112:113] op_sel_hi:[1,0,1]
	v_cvt_pk_bf16_f32 v56, v56, v57
	v_cvt_pk_bf16_f32 v57, v58, v59
	global_store_dwordx2 v[68:69], v[56:57], off offset:544
	s_waitcnt vmcnt(18)
	v_pk_fma_f32 v[56:57], v[64:65], v[2:3], v[114:115] op_sel_hi:[1,0,1]
	v_pk_fma_f32 v[58:59], v[66:67], v[2:3], v[116:117] op_sel_hi:[1,0,1]
	v_cvt_pk_bf16_f32 v56, v56, v57
	v_cvt_pk_bf16_f32 v57, v58, v59
	global_store_dwordx2 v[68:69], v[56:57], off offset:576
	s_waitcnt vmcnt(18)
	v_pk_fma_f32 v[56:57], v[60:61], v[2:3], v[118:119] op_sel_hi:[1,0,1]
	v_pk_fma_f32 v[2:3], v[62:63], v[2:3], v[120:121] op_sel_hi:[1,0,1]
	v_cvt_pk_bf16_f32 v56, v56, v57
	v_cvt_pk_bf16_f32 v57, v2, v3
	global_store_dwordx2 v[68:69], v[56:57], off offset:608
	s_waitcnt vmcnt(18)
	v_mul_f32_e32 v2, 0xbfb8aa3b, v105
	v_exp_f32_e32 v2, v2
	s_nop 0
	v_add_f32_e32 v2, 1.0, v2
	v_rcp_f32_e32 v2, v2
	s_nop 0
	v_div_scale_f32 v3, s[2:3], v4, v4, v2
	v_rcp_f32_e32 v7, v3
	s_nop 0
	v_fma_f32 v56, -v3, v7, 1.0
	v_fmac_f32_e32 v7, v56, v7
	v_div_scale_f32 v56, vcc, v2, v4, v2
	v_mul_f32_e32 v57, v56, v7
	v_fma_f32 v58, -v3, v57, v56
	v_fmac_f32_e32 v57, v58, v7
	v_fma_f32 v3, -v3, v57, v56
	v_div_fmas_f32 v3, v3, v7, v57
	v_div_fixup_f32 v4, v3, v4, v2
	v_lshl_add_u64 v[2:3], s[36:37], 0, v[216:217]
	v_lshl_add_u64 v[2:3], v[2:3], 0, v[128:129]
	v_lshl_add_u64 v[2:3], v[2:3], 0, v[0:1]
	s_waitcnt vmcnt(17)
	v_pk_fma_f32 v[52:53], v[52:53], v[4:5], v[122:123] op_sel_hi:[1,0,1]
	v_pk_fma_f32 v[54:55], v[54:55], v[4:5], v[124:125] op_sel_hi:[1,0,1]
	v_cvt_pk_bf16_f32 v52, v52, v53
	v_cvt_pk_bf16_f32 v53, v54, v55
	global_store_dwordx2 v[2:3], v[52:53], off offset:512
	s_waitcnt vmcnt(17)
	v_pk_fma_f32 v[48:49], v[48:49], v[4:5], v[130:131] op_sel_hi:[1,0,1]
	v_pk_fma_f32 v[50:51], v[50:51], v[4:5], v[132:133] op_sel_hi:[1,0,1]
	v_cvt_pk_bf16_f32 v48, v48, v49
	v_cvt_pk_bf16_f32 v49, v50, v51
	global_store_dwordx2 v[2:3], v[48:49], off offset:544
	s_waitcnt vmcnt(17)
	v_pk_fma_f32 v[44:45], v[44:45], v[4:5], v[134:135] op_sel_hi:[1,0,1]
	v_pk_fma_f32 v[46:47], v[46:47], v[4:5], v[136:137] op_sel_hi:[1,0,1]
	v_cvt_pk_bf16_f32 v44, v44, v45
	v_cvt_pk_bf16_f32 v45, v46, v47
	global_store_dwordx2 v[2:3], v[44:45], off offset:576
	s_waitcnt vmcnt(17)
	v_pk_fma_f32 v[40:41], v[40:41], v[4:5], v[158:159] op_sel_hi:[1,0,1]
	v_pk_fma_f32 v[42:43], v[42:43], v[4:5], v[160:161] op_sel_hi:[1,0,1]
	v_cvt_pk_bf16_f32 v40, v40, v41
	v_cvt_pk_bf16_f32 v41, v42, v43
	global_store_dwordx2 v[2:3], v[40:41], off offset:608
	s_waitcnt vmcnt(17)
	v_mul_f32_e32 v2, 0xbfb8aa3b, v126
	v_exp_f32_e32 v2, v2
	s_nop 0
	v_add_f32_e32 v2, 1.0, v2
	v_rcp_f32_e32 v2, v2
	s_nop 0
	v_div_scale_f32 v3, s[2:3], v6, v6, v2
	v_rcp_f32_e32 v4, v3
	s_nop 0
	v_fma_f32 v7, -v3, v4, 1.0
	v_fmac_f32_e32 v4, v7, v4
	v_div_scale_f32 v7, vcc, v2, v6, v2
	v_mul_f32_e32 v40, v7, v4
	v_fma_f32 v41, -v3, v40, v7
	v_fmac_f32_e32 v40, v41, v4
	v_fma_f32 v3, -v3, v40, v7
	v_div_fmas_f32 v3, v3, v4, v40
	v_div_fixup_f32 v2, v3, v6, v2
	v_lshl_add_u64 v[6:7], s[36:37], 0, v[204:205]
	v_lshl_add_u64 v[6:7], v[6:7], 0, v[128:129]
	v_lshl_add_u64 v[6:7], v[6:7], 0, v[0:1]
	s_waitcnt vmcnt(16)
	v_pk_fma_f32 v[36:37], v[36:37], v[2:3], v[162:163] op_sel_hi:[1,0,1]
	v_pk_fma_f32 v[38:39], v[38:39], v[2:3], v[164:165] op_sel_hi:[1,0,1]
	v_cvt_pk_bf16_f32 v36, v36, v37
	v_cvt_pk_bf16_f32 v37, v38, v39
	global_store_dwordx2 v[6:7], v[36:37], off offset:512
	s_waitcnt vmcnt(16)
	v_pk_fma_f32 v[32:33], v[32:33], v[2:3], v[166:167] op_sel_hi:[1,0,1]
	v_pk_fma_f32 v[34:35], v[34:35], v[2:3], v[168:169] op_sel_hi:[1,0,1]
	v_cvt_pk_bf16_f32 v32, v32, v33
	v_cvt_pk_bf16_f32 v33, v34, v35
	global_store_dwordx2 v[6:7], v[32:33], off offset:544
	s_waitcnt vmcnt(16)
	v_pk_fma_f32 v[28:29], v[28:29], v[2:3], v[170:171] op_sel_hi:[1,0,1]
	v_pk_fma_f32 v[30:31], v[30:31], v[2:3], v[172:173] op_sel_hi:[1,0,1]
	v_cvt_pk_bf16_f32 v28, v28, v29
	v_cvt_pk_bf16_f32 v29, v30, v31
	global_store_dwordx2 v[6:7], v[28:29], off offset:576
	s_waitcnt vmcnt(16)
	v_pk_fma_f32 v[24:25], v[24:25], v[2:3], v[174:175] op_sel_hi:[1,0,1]
	v_pk_fma_f32 v[2:3], v[26:27], v[2:3], v[176:177] op_sel_hi:[1,0,1]
	v_cvt_pk_bf16_f32 v24, v24, v25
	v_cvt_pk_bf16_f32 v25, v2, v3
	global_store_dwordx2 v[6:7], v[24:25], off offset:608
	s_waitcnt vmcnt(16)
	v_mul_f32_e32 v2, 0xbfb8aa3b, v127
	v_exp_f32_e32 v2, v2
	s_nop 0
	v_add_f32_e32 v2, 1.0, v2
	v_rcp_f32_e32 v2, v2
	s_nop 0
	v_div_scale_f32 v3, s[2:3], v5, v5, v2
	v_rcp_f32_e32 v4, v3
	s_nop 0
	v_fma_f32 v6, -v3, v4, 1.0
	v_fmac_f32_e32 v4, v6, v4
	v_div_scale_f32 v6, vcc, v2, v5, v2
	v_mul_f32_e32 v7, v6, v4
	v_fma_f32 v24, -v3, v7, v6
	v_fmac_f32_e32 v7, v24, v4
	v_fma_f32 v3, -v3, v7, v6
	v_div_fmas_f32 v3, v3, v4, v7
	v_div_fixup_f32 v2, v3, v5, v2
	v_lshl_add_u64 v[4:5], s[36:37], 0, v[206:207]
	v_lshl_add_u64 v[4:5], v[4:5], 0, v[128:129]
	v_lshl_add_u64 v[0:1], v[4:5], 0, v[0:1]
	s_waitcnt vmcnt(15)
	v_pk_fma_f32 v[4:5], v[20:21], v[2:3], v[178:179] op_sel_hi:[1,0,1]
	v_pk_fma_f32 v[6:7], v[22:23], v[2:3], v[180:181] op_sel_hi:[1,0,1]
	v_cvt_pk_bf16_f32 v4, v4, v5
	v_cvt_pk_bf16_f32 v5, v6, v7
	global_store_dwordx2 v[0:1], v[4:5], off offset:512
	s_waitcnt vmcnt(15)
	v_pk_fma_f32 v[4:5], v[16:17], v[2:3], v[182:183] op_sel_hi:[1,0,1]
	v_pk_fma_f32 v[6:7], v[18:19], v[2:3], v[184:185] op_sel_hi:[1,0,1]
	v_cvt_pk_bf16_f32 v4, v4, v5
	v_cvt_pk_bf16_f32 v5, v6, v7
	global_store_dwordx2 v[0:1], v[4:5], off offset:544
	s_waitcnt vmcnt(15)
	v_pk_fma_f32 v[4:5], v[12:13], v[2:3], v[186:187] op_sel_hi:[1,0,1]
	v_pk_fma_f32 v[6:7], v[14:15], v[2:3], v[188:189] op_sel_hi:[1,0,1]
	v_cvt_pk_bf16_f32 v4, v4, v5
	v_cvt_pk_bf16_f32 v5, v6, v7
	global_store_dwordx2 v[0:1], v[4:5], off offset:576
	s_waitcnt vmcnt(15)
	v_pk_fma_f32 v[4:5], v[8:9], v[2:3], v[248:249] op_sel_hi:[1,0,1]
	v_pk_fma_f32 v[2:3], v[10:11], v[2:3], v[250:251] op_sel_hi:[1,0,1]
	v_cvt_pk_bf16_f32 v4, v4, v5
	v_cvt_pk_bf16_f32 v5, v2, v3
	global_store_dwordx2 v[0:1], v[4:5], off offset:608

.LBB0_760:
	s_setprio 0
	s_and_b32 s2, s42, 30
	s_lshl_b32 s70, 1, s2
	s_cmp_lg_u32 s2, 0
	s_cbranch_scc1 .Lsel_have_words
	s_lshr_b32 s2, s42, 3
	s_and_b32 s2, s2, 0x1ffffffc
	v_add_u32_e32 v248, s2, v245
	ds_read2_b32 v[250:251], v248 offset1:32
	ds_read_b32 v249, v248 offset:256
	ds_read_b32 v248, v248 offset:384
	s_waitcnt lgkmcnt(0)
.Lsel_have_words:
	v_and_b32_e32 v0, s70, v250
	v_cmp_ne_u32_e64 s[50:51], 0, v0
	v_and_b32_e32 v0, s70, v251
	v_cmp_ne_u32_e64 s[48:49], 0, v0
	v_and_b32_e32 v0, s70, v249
	v_cmp_ne_u32_e64 s[46:47], 0, v0
	v_and_b32_e32 v0, s70, v248
	v_cmp_ne_u32_e64 s[42:43], 0, v0
	s_mov_b64 s[86:87], s[50:51]
	s_mov_b64 s[88:89], s[48:49]
	s_mov_b64 s[90:91], s[46:47]
	s_mov_b64 s[92:93], s[42:43]
	s_or_b64 s[2:3], s[48:49], s[50:51]
	s_or_b64 s[2:3], s[2:3], s[46:47]
	s_or_b64 s[2:3], s[2:3], s[42:43]
	s_cmp_eq_u64 s[2:3], 0
	s_cbranch_scc1 .LBB0_810
	s_setprio 1
	ds_read_b128 v[182:185], v246
	ds_read_b128 v[178:181], v246 offset:2048
	ds_read_b128 v[186:189], v247
	ds_read_b128 v[174:177], v247 offset:2048
	ds_read_b128 v[158:161], v244 offset:4096
	ds_read_b128 v[162:165], v244 offset:5120
	ds_read_b128 v[166:169], v244 offset:6144
	ds_read_b128 v[170:173], v244 offset:7168
	s_add_i32 s2, s28, 0xfffffeff
	s_cmp_le_i32 s2, s26
	s_cselect_b64 s[2:3], -1, 0
	v_cndmask_b32_e64 v0, 0, 1, s[2:3]
	s_cmp_eq_u64 s[50:51], 0
	v_cmp_ne_u32_e64 s[44:45], 1, v0
	s_cbranch_scc1 .LBB0_767
	v_cndmask_b32_e64 v190, v194, 0, s[50:51]
	v_cndmask_b32_e64 v191, v194, 0, s[50:51]
	v_cndmask_b32_e64 v192, v194, 0, s[50:51]
	v_cndmask_b32_e64 v193, v194, 0, s[50:51]
	s_nop 0
	s_waitcnt lgkmcnt(7)
	v_mfma_f32_16x16x32_bf16 v[0:3], v[182:185], v[104:107], v[190:193]
	s_and_b64 vcc, exec, s[44:45]
	s_mov_b64 s[64:65], -1
	s_waitcnt lgkmcnt(6)
	v_mfma_f32_16x16x32_bf16 v[4:7], v[178:181], v[104:107], v[190:193]
	s_waitcnt lgkmcnt(5)
	v_mfma_f32_16x16x32_bf16 v[0:3], v[186:189], v[108:111], v[0:3]
	s_waitcnt lgkmcnt(4)
	v_mfma_f32_16x16x32_bf16 v[4:7], v[174:177], v[108:111], v[4:7]
	s_nop 5
	v_exp_f32_e32 v0, v0
	v_exp_f32_e32 v1, v1
	v_exp_f32_e32 v2, v2
	v_exp_f32_e32 v3, v3
	v_exp_f32_e32 v4, v4
	v_exp_f32_e32 v5, v5
	v_exp_f32_e32 v6, v6
	v_exp_f32_e32 v7, v7
	s_cbranch_vccz .LBB0_766

.LBB0_815:
	s_setprio 0
	s_add_i32 s2, s27, -3
	s_lshl_b32 s64, 1, s2
	v_and_b32_e32 v0, s64, v250
	v_cmp_ne_u32_e64 s[50:51], 0, v0
	v_and_b32_e32 v0, s64, v251
	v_cmp_ne_u32_e64 s[48:49], 0, v0
	v_and_b32_e32 v0, s64, v249
	v_cmp_ne_u32_e64 s[46:47], 0, v0
	v_and_b32_e32 v0, s64, v248
	v_cmp_ne_u32_e64 s[42:43], 0, v0
	s_mov_b64 s[86:87], s[50:51]
	s_mov_b64 s[88:89], s[48:49]
	s_mov_b64 s[90:91], s[46:47]
	s_mov_b64 s[92:93], s[42:43]
	s_or_b64 s[2:3], s[48:49], s[50:51]
	s_or_b64 s[2:3], s[2:3], s[46:47]
	s_or_b64 s[2:3], s[2:3], s[42:43]
	s_cmp_eq_u64 s[2:3], 0
	s_cbranch_scc1 .LBB0_754
	s_setprio 1
	ds_read_b128 v[182:185], v246 offset:16384
	ds_read_b128 v[178:181], v246 offset:18432
	ds_read_b128 v[186:189], v247 offset:16384
	ds_read_b128 v[174:177], v247 offset:18432
	ds_read_b128 v[158:161], v244 offset:20480
	ds_read_b128 v[162:165], v244 offset:21504
	ds_read_b128 v[166:169], v244 offset:22528
	ds_read_b128 v[170:173], v244 offset:23552
	s_add_i32 s2, s28, 0xffffff3f
	s_cmp_le_i32 s2, s26
	s_cselect_b64 s[2:3], -1, 0
	v_cndmask_b32_e64 v0, 0, 1, s[2:3]
	s_cmp_eq_u64 s[50:51], 0
	v_cmp_ne_u32_e64 s[44:45], 1, v0
	s_cbranch_scc1 .LBB0_822
	v_cndmask_b32_e64 v190, v194, 0, s[50:51]
	v_cndmask_b32_e64 v191, v194, 0, s[50:51]
	v_cndmask_b32_e64 v192, v194, 0, s[50:51]
	v_cndmask_b32_e64 v193, v194, 0, s[50:51]
	s_nop 0
	s_waitcnt lgkmcnt(7)
	v_mfma_f32_16x16x32_bf16 v[0:3], v[182:185], v[104:107], v[190:193]
	s_and_b64 vcc, exec, s[44:45]
	s_mov_b64 s[40:41], -1
	s_waitcnt lgkmcnt(6)
	v_mfma_f32_16x16x32_bf16 v[4:7], v[178:181], v[104:107], v[190:193]
	s_waitcnt lgkmcnt(5)
	v_mfma_f32_16x16x32_bf16 v[0:3], v[186:189], v[108:111], v[0:3]
	s_waitcnt lgkmcnt(4)
	v_mfma_f32_16x16x32_bf16 v[4:7], v[174:177], v[108:111], v[4:7]
	s_nop 5
	v_exp_f32_e32 v0, v0
	v_exp_f32_e32 v1, v1
	v_exp_f32_e32 v2, v2
	v_exp_f32_e32 v3, v3
	v_exp_f32_e32 v4, v4
	v_exp_f32_e32 v5, v5
	v_exp_f32_e32 v6, v6
	v_exp_f32_e32 v7, v7
	s_cbranch_vccz .LBB0_821

.Lsel_have_words2:
	v_and_b32_e32 v0, s70, v250
	v_cmp_ne_u32_e64 s[50:51], 0, v0
	v_and_b32_e32 v0, s70, v251
	v_cmp_ne_u32_e64 s[48:49], 0, v0
	v_and_b32_e32 v0, s70, v249
	v_cmp_ne_u32_e64 s[46:47], 0, v0
	v_and_b32_e32 v0, s70, v248
	v_cmp_ne_u32_e64 s[42:43], 0, v0
	s_mov_b64 s[86:87], s[50:51]
	s_mov_b64 s[88:89], s[48:49]
	s_mov_b64 s[90:91], s[46:47]
	s_mov_b64 s[92:93], s[42:43]
	s_or_b64 s[2:3], s[48:49], s[50:51]
	s_or_b64 s[2:3], s[2:3], s[46:47]
	s_or_b64 s[2:3], s[2:3], s[42:43]
	s_cmp_eq_u64 s[2:3], 0
	s_cbranch_scc1 .LB2_810
	s_setprio 1
	ds_read_b128 v[182:185], v246 offset:32768
	ds_read_b128 v[178:181], v246 offset:34816
	ds_read_b128 v[186:189], v247 offset:32768
	ds_read_b128 v[174:177], v247 offset:34816
	ds_read_b128 v[158:161], v244 offset:36864
	ds_read_b128 v[162:165], v244 offset:37888
	ds_read_b128 v[166:169], v244 offset:38912
	ds_read_b128 v[170:173], v244 offset:39936
	s_add_i32 s2, s28, 0xfffffeff
	s_cmp_le_i32 s2, s26
	s_cselect_b64 s[2:3], -1, 0
	v_cndmask_b32_e64 v0, 0, 1, s[2:3]
	s_cmp_eq_u64 s[50:51], 0
	v_cmp_ne_u32_e64 s[44:45], 1, v0
	s_cbranch_scc1 .LB2_767
	v_cndmask_b32_e64 v190, v194, 0, s[50:51]
	v_cndmask_b32_e64 v191, v194, 0, s[50:51]
	v_cndmask_b32_e64 v192, v194, 0, s[50:51]
	v_cndmask_b32_e64 v193, v194, 0, s[50:51]
	s_nop 0
	s_waitcnt lgkmcnt(7)
	v_mfma_f32_16x16x32_bf16 v[0:3], v[182:185], v[104:107], v[190:193]
	s_and_b64 vcc, exec, s[44:45]
	s_mov_b64 s[64:65], -1
	s_waitcnt lgkmcnt(6)
	v_mfma_f32_16x16x32_bf16 v[4:7], v[178:181], v[104:107], v[190:193]
	s_waitcnt lgkmcnt(5)
	v_mfma_f32_16x16x32_bf16 v[0:3], v[186:189], v[108:111], v[0:3]
	s_waitcnt lgkmcnt(4)
	v_mfma_f32_16x16x32_bf16 v[4:7], v[174:177], v[108:111], v[4:7]
	s_nop 5
	v_exp_f32_e32 v0, v0
	v_exp_f32_e32 v1, v1
	v_exp_f32_e32 v2, v2
	v_exp_f32_e32 v3, v3
	v_exp_f32_e32 v4, v4
	v_exp_f32_e32 v5, v5
	v_exp_f32_e32 v6, v6
	v_exp_f32_e32 v7, v7
	s_cbranch_vccz .LB2_766

.LB2_815:
	s_setprio 0
	s_add_i32 s2, s27, -3
	s_lshl_b32 s64, 1, s2
	v_and_b32_e32 v0, s64, v250
	v_cmp_ne_u32_e64 s[50:51], 0, v0
	v_and_b32_e32 v0, s64, v251
	v_cmp_ne_u32_e64 s[48:49], 0, v0
	v_and_b32_e32 v0, s64, v249
	v_cmp_ne_u32_e64 s[46:47], 0, v0
	v_and_b32_e32 v0, s64, v248
	v_cmp_ne_u32_e64 s[42:43], 0, v0
	s_mov_b64 s[86:87], s[50:51]
	s_mov_b64 s[88:89], s[48:49]
	s_mov_b64 s[90:91], s[46:47]
	s_mov_b64 s[92:93], s[42:43]
	s_or_b64 s[2:3], s[48:49], s[50:51]
	s_or_b64 s[2:3], s[2:3], s[46:47]
	s_or_b64 s[2:3], s[2:3], s[42:43]
	s_cmp_eq_u64 s[2:3], 0
	s_cbranch_scc1 .LB2_754
	s_setprio 1
	ds_read_b128 v[182:185], v246 offset:49152
	ds_read_b128 v[178:181], v246 offset:51200
	ds_read_b128 v[186:189], v247 offset:49152
	ds_read_b128 v[174:177], v247 offset:51200
	ds_read_b128 v[158:161], v244 offset:53248
	ds_read_b128 v[162:165], v244 offset:54272
	ds_read_b128 v[166:169], v244 offset:55296
	ds_read_b128 v[170:173], v244 offset:56320
	s_add_i32 s2, s28, 0xffffff3f
	s_cmp_le_i32 s2, s26
	s_cselect_b64 s[2:3], -1, 0
	v_cndmask_b32_e64 v0, 0, 1, s[2:3]
	s_cmp_eq_u64 s[50:51], 0
	v_cmp_ne_u32_e64 s[44:45], 1, v0
	s_cbranch_scc1 .LB2_822
	v_cndmask_b32_e64 v190, v194, 0, s[50:51]
	v_cndmask_b32_e64 v191, v194, 0, s[50:51]
	v_cndmask_b32_e64 v192, v194, 0, s[50:51]
	v_cndmask_b32_e64 v193, v194, 0, s[50:51]
	s_nop 0
	s_waitcnt lgkmcnt(7)
	v_mfma_f32_16x16x32_bf16 v[0:3], v[182:185], v[104:107], v[190:193]
	s_and_b64 vcc, exec, s[44:45]
	s_mov_b64 s[40:41], -1
	s_waitcnt lgkmcnt(6)
	v_mfma_f32_16x16x32_bf16 v[4:7], v[178:181], v[104:107], v[190:193]
	s_waitcnt lgkmcnt(5)
	v_mfma_f32_16x16x32_bf16 v[0:3], v[186:189], v[108:111], v[0:3]
	s_waitcnt lgkmcnt(4)
	v_mfma_f32_16x16x32_bf16 v[4:7], v[174:177], v[108:111], v[4:7]
	s_nop 5
	v_exp_f32_e32 v0, v0
	v_exp_f32_e32 v1, v1
	v_exp_f32_e32 v2, v2
	v_exp_f32_e32 v3, v3
	v_exp_f32_e32 v4, v4
	v_exp_f32_e32 v5, v5
	v_exp_f32_e32 v6, v6
	v_exp_f32_e32 v7, v7
	s_cbranch_vccz .LB2_821
